# final-norm output stores without the nontemporal hint
# baseline (speedup 1.0000x reference)
; __device__ __forceinline__ float rinv_from(u64 v) { return rsqrtf((float)v * (1.0f / 16777216.0f) * (1.0f / 1024.0f) + RMS_EPS); }
; __device__ __forceinline__ void final_phase(const Ctx& C) {
;     ...
;     for (int m0 = gw * 4; m0 < M; m0 += NGW * 4) {
;         u32x2 v[4][4]; float ri[4];
; #pragma unroll
;         for (int r = 0; r < 4; ++r) { ri[r] = rinv_from(__hip_atomic_load(ssq + m0 + r, __ATOMIC_RELAXED, __HIP_MEMORY_SCOPE_AGENT)); const u32x2* xi = (const u32x2*)(XB + (size_t)(m0 + r) * DM) + C.lane;
; #pragma unroll
;             for (int j = 0; j < 4; ++j) v[r][j] = xi[64 * j]; }
.LBB0_664:
	v_add_co_u32_e32 v22, vcc, s21, v16
	v_lshl_add_u64 v[20:21], v[18:19], 0, s[6:7]
	s_nop 0
	v_addc_co_u32_e32 v23, vcc, -1, v17, vcc
	v_add_co_u32_e32 v24, vcc, s22, v16
	s_add_u32 s0, s9, s6
	s_nop 0
	v_addc_co_u32_e32 v25, vcc, -1, v17, vcc
	v_add_co_u32_e32 v92, vcc, s23, v16
	s_addc_u32 s1, s18, s7
	s_nop 0
	v_addc_co_u32_e32 v93, vcc, -1, v17, vcc
	v_add_co_u32_e32 v28, vcc, s19, v20
	s_add_i32 s8, s8, s10
	s_nop 0
	v_addc_co_u32_e32 v29, vcc, 0, v21, vcc
	v_add_co_u32_e32 v20, vcc, s20, v20
	s_add_u32 s9, s9, s16
	s_nop 0
	v_addc_co_u32_e32 v21, vcc, 0, v21, vcc
	global_load_dwordx2 v[30:31], v26, s[0:1] sc1
	global_load_dwordx2 v[32:33], v[20:21], off offset:-4096
	global_load_dwordx2 v[34:35], v[28:29], off offset:512
	global_load_dwordx2 v[36:37], v[28:29], off offset:1024
	global_load_dwordx2 v[38:39], v[28:29], off offset:1536
	global_load_dwordx2 v[40:41], v26, s[0:1] offset:8 sc1
	global_load_dwordx2 v[42:43], v[28:29], off offset:2048
	global_load_dwordx2 v[44:45], v[28:29], off offset:2560
	global_load_dwordx2 v[46:47], v[28:29], off offset:3072
	global_load_dwordx2 v[48:49], v[28:29], off offset:3584
	global_load_dwordx2 v[50:51], v26, s[0:1] offset:16 sc1
	global_load_dwordx2 v[52:53], v[20:21], off
	global_load_dwordx2 v[54:55], v[20:21], off offset:512
	global_load_dwordx2 v[56:57], v[20:21], off offset:1024
	global_load_dwordx2 v[58:59], v[20:21], off offset:1536
	global_load_dwordx2 v[28:29], v26, s[0:1] offset:24 sc1
	global_load_dwordx2 v[60:61], v[20:21], off offset:2048
	global_load_dwordx2 v[62:63], v[20:21], off offset:2560
	global_load_dwordx2 v[64:65], v[20:21], off offset:3072
	global_load_dwordx2 v[66:67], v[20:21], off offset:3584
	s_addc_u32 s18, s18, s17
	v_lshl_add_u64 v[18:19], v[18:19], 0, s[14:15]
	s_cmp_lt_i32 s8, 0x10000
	s_waitcnt vmcnt(19)
	v_ffbh_u32_e32 v100, v31
	v_min_u32_e32 v100, 32, v100
	v_lshlrev_b64 v[30:31], v100, v[30:31]
	v_min_u32_e32 v30, 1, v30
	v_or_b32_e32 v30, v31, v30
	s_waitcnt vmcnt(14)
	v_ffbh_u32_e32 v101, v41
	v_min_u32_e32 v101, 32, v101
	v_lshlrev_b64 v[40:41], v101, v[40:41]
	v_min_u32_e32 v40, 1, v40
	v_or_b32_e32 v31, v41, v40
	s_waitcnt vmcnt(9)
	v_ffbh_u32_e32 v102, v51
	v_min_u32_e32 v102, 32, v102
	v_lshlrev_b64 v[50:51], v102, v[50:51]
	v_min_u32_e32 v50, 1, v50
	v_or_b32_e32 v40, v51, v50
	v_sub_u32_e32 v100, 32, v100
	s_waitcnt vmcnt(4)
	v_ffbh_u32_e32 v103, v29
	v_min_u32_e32 v103, 32, v103
	v_lshlrev_b64 v[28:29], v103, v[28:29]
	v_min_u32_e32 v28, 1, v28
	v_or_b32_e32 v28, v29, v28
	v_cvt_f32_u32_e32 v29, v30
	v_cvt_f32_u32_e32 v30, v31
	v_cvt_f32_u32_e32 v31, v40
	v_cvt_f32_u32_e32 v28, v28
	v_sub_u32_e32 v101, 32, v101
	v_sub_u32_e32 v102, 32, v102
	v_sub_u32_e32 v103, 32, v103
	v_ldexp_f32 v29, v29, v100
	v_ldexp_f32 v30, v30, v101
	v_ldexp_f32 v31, v31, v102
	v_ldexp_f32 v28, v28, v103
	v_mul_f32_e32 v29, 0x33800000, v29
	v_mul_f32_e32 v30, 0x33800000, v30
	v_mul_f32_e32 v31, 0x33800000, v31
	v_mul_f32_e32 v28, 0x33800000, v28
	v_fmamk_f32 v29, v29, 0x3a800000, v27
	v_fmamk_f32 v30, v30, 0x3a800000, v27
	v_fmamk_f32 v31, v31, 0x3a800000, v27
	v_fmamk_f32 v28, v28, 0x3a800000, v27
	v_mul_f32_e32 v40, 0x4b800000, v29
	v_cmp_gt_f32_e64 s[4:5], s11, v29
	v_mul_f32_e32 v41, 0x4b800000, v30
	v_cmp_gt_f32_e32 vcc, s11, v30
	v_mul_f32_e32 v50, 0x4b800000, v31
	v_cmp_gt_f32_e64 s[0:1], s11, v31
	v_mul_f32_e32 v51, 0x4b800000, v28
	v_cmp_gt_f32_e64 s[2:3], s11, v28
	v_cndmask_b32_e64 v29, v29, v40, s[4:5]
	v_cndmask_b32_e32 v30, v30, v41, vcc
	v_cndmask_b32_e64 v31, v31, v50, s[0:1]
	v_cndmask_b32_e64 v28, v28, v51, s[2:3]
	v_rsq_f32_e32 v29, v29
	v_rsq_f32_e32 v30, v30
	v_rsq_f32_e32 v31, v31
	v_rsq_f32_e32 v41, v28
	v_mul_f32_e32 v28, 0x45800000, v29
	v_lshlrev_b32_e32 v20, 16, v32
	v_and_b32_e32 v21, 0xffff0000, v32
	v_lshlrev_b32_e32 v32, 16, v33
	v_and_b32_e32 v33, 0xffff0000, v33
	v_mul_f32_e32 v40, 0x45800000, v30
	v_mul_f32_e32 v50, 0x45800000, v31
	v_mul_f32_e32 v51, 0x45800000, v41
	v_cndmask_b32_e64 v28, v29, v28, s[4:5]
	v_lshlrev_b32_e32 v68, 16, v34
	v_and_b32_e32 v69, 0xffff0000, v34
	v_lshlrev_b32_e32 v34, 16, v35
	v_and_b32_e32 v35, 0xffff0000, v35
	v_lshlrev_b32_e32 v70, 16, v36
	v_and_b32_e32 v71, 0xffff0000, v36
	v_lshlrev_b32_e32 v36, 16, v37
	v_and_b32_e32 v37, 0xffff0000, v37
	v_lshlrev_b32_e32 v72, 16, v38
	v_and_b32_e32 v73, 0xffff0000, v38
	v_lshlrev_b32_e32 v38, 16, v39
	v_and_b32_e32 v39, 0xffff0000, v39
	v_lshlrev_b32_e32 v74, 16, v42
	v_and_b32_e32 v75, 0xffff0000, v42
	v_lshlrev_b32_e32 v42, 16, v43
	v_and_b32_e32 v43, 0xffff0000, v43
	v_lshlrev_b32_e32 v76, 16, v44
	v_and_b32_e32 v77, 0xffff0000, v44
	v_lshlrev_b32_e32 v44, 16, v45
	v_and_b32_e32 v45, 0xffff0000, v45
	v_lshlrev_b32_e32 v78, 16, v46
	v_and_b32_e32 v79, 0xffff0000, v46
	v_lshlrev_b32_e32 v46, 16, v47
	v_and_b32_e32 v47, 0xffff0000, v47
	v_lshlrev_b32_e32 v80, 16, v48
	v_and_b32_e32 v81, 0xffff0000, v48
	v_lshlrev_b32_e32 v48, 16, v49
	v_and_b32_e32 v49, 0xffff0000, v49
	v_lshlrev_b32_e32 v82, 16, v52
	v_and_b32_e32 v83, 0xffff0000, v52
	v_lshlrev_b32_e32 v52, 16, v53
	v_and_b32_e32 v53, 0xffff0000, v53
	v_lshlrev_b32_e32 v84, 16, v54
	v_and_b32_e32 v85, 0xffff0000, v54
	v_lshlrev_b32_e32 v54, 16, v55
	v_and_b32_e32 v55, 0xffff0000, v55
	v_lshlrev_b32_e32 v86, 16, v56
	v_and_b32_e32 v87, 0xffff0000, v56
	v_lshlrev_b32_e32 v56, 16, v57
	v_and_b32_e32 v57, 0xffff0000, v57
	v_lshlrev_b32_e32 v88, 16, v58
	v_and_b32_e32 v89, 0xffff0000, v58
	v_lshlrev_b32_e32 v58, 16, v59
	v_and_b32_e32 v59, 0xffff0000, v59
	s_waitcnt vmcnt(3)
; __device__ __forceinline__ float bf_lo(unsigned w) { return __uint_as_float(w << 16); }
; __device__ __forceinline__ float bf_hi(unsigned w) { return __uint_as_float(w & 0xffff0000u); }
; __device__ __forceinline__ void final_phase(const Ctx& C) {
;     ...
;         for (int r = 0; r < 4; ++r) { f32x4* xr = (f32x4*)(C.out + (size_t)(m0 + r) * DM) + C.lane;
; #pragma unroll
;             for (int j = 0; j < 4; ++j) __builtin_nontemporal_store((f32x4){bf_lo(v[r][j].x), bf_hi(v[r][j].x), bf_lo(v[r][j].y), bf_hi(v[r][j].y)} * ri[r] * gv[j], xr + 64 * j); }
	v_lshlrev_b32_e32 v90, 16, v60
	v_and_b32_e32 v91, 0xffff0000, v60
	v_lshlrev_b32_e32 v60, 16, v61
	v_and_b32_e32 v61, 0xffff0000, v61
	s_waitcnt vmcnt(2)
	v_lshlrev_b32_e32 v94, 16, v62
	v_and_b32_e32 v95, 0xffff0000, v62
	v_lshlrev_b32_e32 v62, 16, v63
	v_and_b32_e32 v63, 0xffff0000, v63
	s_waitcnt vmcnt(1)
	v_lshlrev_b32_e32 v96, 16, v64
	v_and_b32_e32 v97, 0xffff0000, v64
	v_lshlrev_b32_e32 v64, 16, v65
	v_and_b32_e32 v65, 0xffff0000, v65
	s_waitcnt vmcnt(0)
	v_lshlrev_b32_e32 v98, 16, v66
	v_and_b32_e32 v99, 0xffff0000, v66
	v_lshlrev_b32_e32 v66, 16, v67
	v_and_b32_e32 v67, 0xffff0000, v67
	v_cndmask_b32_e32 v30, v30, v40, vcc
	v_cndmask_b32_e64 v40, v31, v50, s[0:1]
	v_cndmask_b32_e64 v50, v41, v51, s[2:3]
	v_pk_mul_f32 v[20:21], v[28:29], v[20:21] op_sel_hi:[0,1]
	v_pk_mul_f32 v[32:33], v[28:29], v[32:33] op_sel_hi:[0,1]
	v_pk_mul_f32 v[68:69], v[28:29], v[68:69] op_sel_hi:[0,1]
	v_pk_mul_f32 v[34:35], v[28:29], v[34:35] op_sel_hi:[0,1]
	v_pk_mul_f32 v[70:71], v[28:29], v[70:71] op_sel_hi:[0,1]
	v_pk_mul_f32 v[36:37], v[28:29], v[36:37] op_sel_hi:[0,1]
	v_pk_mul_f32 v[72:73], v[28:29], v[72:73] op_sel_hi:[0,1]
	v_pk_mul_f32 v[100:101], v[28:29], v[38:39] op_sel_hi:[0,1]
	v_pk_mul_f32 v[74:75], v[30:31], v[74:75] op_sel_hi:[0,1]
	v_pk_mul_f32 v[102:103], v[30:31], v[42:43] op_sel_hi:[0,1]
	v_pk_mul_f32 v[76:77], v[30:31], v[76:77] op_sel_hi:[0,1]
	v_pk_mul_f32 v[104:105], v[30:31], v[44:45] op_sel_hi:[0,1]
	v_pk_mul_f32 v[78:79], v[30:31], v[78:79] op_sel_hi:[0,1]
	v_pk_mul_f32 v[106:107], v[30:31], v[46:47] op_sel_hi:[0,1]
	v_pk_mul_f32 v[80:81], v[30:31], v[80:81] op_sel_hi:[0,1]
	v_pk_mul_f32 v[108:109], v[30:31], v[48:49] op_sel_hi:[0,1]
	v_pk_mul_f32 v[82:83], v[40:41], v[82:83] op_sel_hi:[0,1]
	v_pk_mul_f32 v[110:111], v[40:41], v[52:53] op_sel_hi:[0,1]
	v_pk_mul_f32 v[84:85], v[40:41], v[84:85] op_sel_hi:[0,1]
	v_pk_mul_f32 v[112:113], v[40:41], v[54:55] op_sel_hi:[0,1]
	v_pk_mul_f32 v[86:87], v[40:41], v[86:87] op_sel_hi:[0,1]
	v_pk_mul_f32 v[114:115], v[40:41], v[56:57] op_sel_hi:[0,1]
	v_pk_mul_f32 v[88:89], v[40:41], v[88:89] op_sel_hi:[0,1]
	v_pk_mul_f32 v[116:117], v[40:41], v[58:59] op_sel_hi:[0,1]
	v_pk_mul_f32 v[90:91], v[50:51], v[90:91] op_sel_hi:[0,1]
	v_pk_mul_f32 v[118:119], v[50:51], v[60:61] op_sel_hi:[0,1]
	v_pk_mul_f32 v[94:95], v[50:51], v[94:95] op_sel_hi:[0,1]
	v_pk_mul_f32 v[120:121], v[50:51], v[62:63] op_sel_hi:[0,1]
	v_pk_mul_f32 v[96:97], v[50:51], v[96:97] op_sel_hi:[0,1]
	v_pk_mul_f32 v[122:123], v[50:51], v[64:65] op_sel_hi:[0,1]
	v_pk_mul_f32 v[98:99], v[50:51], v[98:99] op_sel_hi:[0,1]
	v_pk_mul_f32 v[124:125], v[50:51], v[66:67] op_sel_hi:[0,1]
	v_pk_mul_f32 v[30:31], v[2:3], v[32:33]
	v_pk_mul_f32 v[28:29], v[0:1], v[20:21]
	v_pk_mul_f32 v[34:35], v[6:7], v[34:35]
	v_pk_mul_f32 v[32:33], v[4:5], v[68:69]
	v_pk_mul_f32 v[38:39], v[10:11], v[36:37]
	v_pk_mul_f32 v[36:37], v[8:9], v[70:71]
	v_pk_mul_f32 v[42:43], v[14:15], v[100:101]
	v_pk_mul_f32 v[40:41], v[12:13], v[72:73]
	v_pk_mul_f32 v[46:47], v[2:3], v[102:103]
	v_pk_mul_f32 v[44:45], v[0:1], v[74:75]
	v_pk_mul_f32 v[50:51], v[6:7], v[104:105]
	v_pk_mul_f32 v[48:49], v[4:5], v[76:77]
	v_pk_mul_f32 v[54:55], v[10:11], v[106:107]
	v_pk_mul_f32 v[52:53], v[8:9], v[78:79]
	v_pk_mul_f32 v[58:59], v[14:15], v[108:109]
	v_pk_mul_f32 v[56:57], v[12:13], v[80:81]
	v_pk_mul_f32 v[62:63], v[2:3], v[110:111]
	v_pk_mul_f32 v[60:61], v[0:1], v[82:83]
	v_pk_mul_f32 v[66:67], v[6:7], v[112:113]
	v_pk_mul_f32 v[64:65], v[4:5], v[84:85]
	v_pk_mul_f32 v[70:71], v[10:11], v[114:115]
	v_pk_mul_f32 v[68:69], v[8:9], v[86:87]
	v_pk_mul_f32 v[74:75], v[14:15], v[116:117]
	v_pk_mul_f32 v[72:73], v[12:13], v[88:89]
	v_pk_mul_f32 v[78:79], v[2:3], v[118:119]
	v_pk_mul_f32 v[76:77], v[0:1], v[90:91]
	v_pk_mul_f32 v[82:83], v[6:7], v[120:121]
	v_pk_mul_f32 v[80:81], v[4:5], v[94:95]
	v_pk_mul_f32 v[86:87], v[10:11], v[122:123]
	v_pk_mul_f32 v[84:85], v[8:9], v[96:97]
	v_pk_mul_f32 v[90:91], v[14:15], v[124:125]
	v_pk_mul_f32 v[88:89], v[12:13], v[98:99]
	global_store_dwordx4 v[22:23], v[28:31], off offset:-3072
	global_store_dwordx4 v[22:23], v[32:35], off offset:-2048
	global_store_dwordx4 v[22:23], v[36:39], off offset:-1024
	global_store_dwordx4 v[24:25], v[40:43], off offset:-4096
	global_store_dwordx4 v[24:25], v[44:47], off offset:-3072
	global_store_dwordx4 v[24:25], v[48:51], off offset:-2048
	global_store_dwordx4 v[24:25], v[52:55], off offset:-1024
	global_store_dwordx4 v[24:25], v[56:59], off
	global_store_dwordx4 v[92:93], v[60:63], off offset:-3072
	global_store_dwordx4 v[92:93], v[64:67], off offset:-2048
	global_store_dwordx4 v[92:93], v[68:71], off offset:-1024
	global_store_dwordx4 v[16:17], v[72:75], off offset:-4096
	global_store_dwordx4 v[16:17], v[76:79], off offset:-3072
	global_store_dwordx4 v[16:17], v[80:83], off offset:-2048
	global_store_dwordx4 v[16:17], v[84:87], off offset:-1024
	global_store_dwordx4 v[16:17], v[88:91], off
	v_lshl_add_u64 v[16:17], v[16:17], 0, s[12:13]
	s_cbranch_scc1 .LBB0_664
